# v41: v40 plus attention softmax exponent arguments computed with v_pk_fma_f32 for neighbouring score registers (29 pairs), same fused multiply-add
# speedup vs baseline: 1.0074x; 1.0074x over previous
.LBB0_2411:
	s_or_b64 exec, exec, s[44:45]
	s_waitcnt vmcnt(0)
	s_waitcnt vmcnt(0) lgkmcnt(0)
	ds_write_b128 v179, v[36:39] offset:16384
	ds_write_b128 v180, v[40:43] offset:16384
	ds_write_b128 v183, v[44:47] offset:45056
	v_lshlrev_b32_e32 v36, 4, v59
	s_and_saveexec_b64 s[10:11], s[12:13]
	v_add3_u32 v37, 0, v58, v36
	ds_write_b128 v37, v[124:127] offset:45056
	s_or_b64 exec, exec, s[10:11]
	v_max_f32_e32 v40, 0xf149f2ca, v2
	v_cndmask_b32_e32 v185, v40, v171, vcc
	v_and_b32_e32 v37, 63, v54
	v_mul_f32_e32 v2, 0xbdd53b94, v185
	v_pk_fma_f32 v[20:21], v[20:21], s[34:35], v[2:3] op_sel_hi:[1,0,0]
	v_pk_fma_f32 v[22:23], v[22:23], s[34:35], v[2:3] op_sel_hi:[1,0,0]
	v_pk_fma_f32 v[24:25], v[24:25], s[34:35], v[2:3] op_sel_hi:[1,0,0]
	v_pk_fma_f32 v[26:27], v[26:27], s[34:35], v[2:3] op_sel_hi:[1,0,0]
	v_pk_fma_f32 v[28:29], v[28:29], s[34:35], v[2:3] op_sel_hi:[1,0,0]
	v_pk_fma_f32 v[30:31], v[30:31], s[34:35], v[2:3] op_sel_hi:[1,0,0]
	v_pk_fma_f32 v[32:33], v[32:33], s[34:35], v[2:3] op_sel_hi:[1,0,0]
	v_pk_fma_f32 v[34:35], v[34:35], s[34:35], v[2:3] op_sel_hi:[1,0,0]
	v_pk_fma_f32 v[132:133], v[18:19], s[34:35], v[2:3] op_sel_hi:[1,0,0]
	v_pk_fma_f32 v[138:139], v[16:17], s[34:35], v[2:3] op_sel_hi:[1,0,0]
	v_pk_fma_f32 v[142:143], v[14:15], s[34:35], v[2:3] op_sel_hi:[1,0,0]
	v_pk_fma_f32 v[128:129], v[12:13], s[34:35], v[2:3] op_sel_hi:[1,0,0]
	v_pk_fma_f32 v[130:131], v[10:11], s[34:35], v[2:3] op_sel_hi:[1,0,0]
	v_pk_fma_f32 v[134:135], v[8:9], s[34:35], v[2:3] op_sel_hi:[1,0,0]
	v_pk_fma_f32 v[136:137], v[6:7], s[34:35], v[2:3] op_sel_hi:[1,0,0]
	v_pk_fma_f32 v[140:141], v[4:5], s[34:35], v[2:3] op_sel_hi:[1,0,0]
	v_and_b32_e32 v2, 0x3fffffc0, v54
	v_lshlrev_b32_e32 v4, 4, v37
	v_exp_f32_e32 v150, v20
	v_sub_f32_e32 v20, 0xf149f2ca, v40
	v_lshl_add_u32 v157, v2, 2, 0
	v_lshlrev_b32_e32 v2, 3, v37
	v_and_b32_e32 v4, 0xc0, v4
	v_lshlrev_b32_e32 v5, 1, v37
	v_mad_i64_i32 v[38:39], s[0:1], v57, s55, 0
	v_mul_f32_e32 v20, 0x3dd53b94, v20
	v_and_or_b32 v4, v2, 24, v4
	v_and_b32_e32 v5, 32, v5
	v_and_b32_e32 v2, 0x100, v2
	v_exp_f32_e32 v20, v20
	v_or3_b32 v2, v4, v5, v2
	s_add_i32 s0, 0, 0x4000
	v_mov_b64_e32 v[4:5], s[14:15]
	v_add_u32_e32 v176, s0, v2
	v_mad_i64_i32 v[4:5], s[0:1], v55, s55, v[4:5]
	v_add_u32_e32 v178, 0, v2
	v_lshl_add_u64 v[158:159], v[4:5], 0, v[52:53]
	v_lshl_add_u64 v[4:5], s[14:15], 0, v[38:39]
	v_and_b32_e32 v2, 15, v54
	v_exp_f32_e32 v151, v21
	v_exp_f32_e32 v152, v22
	v_exp_f32_e32 v153, v23
	v_exp_f32_e32 v154, v24
	v_exp_f32_e32 v165, v25
	v_exp_f32_e32 v166, v26
	v_exp_f32_e32 v168, v27
	v_exp_f32_e32 v145, v28
	v_exp_f32_e32 v146, v29
	v_exp_f32_e32 v147, v30
	v_exp_f32_e32 v148, v31
	v_exp_f32_e32 v149, v32
	v_exp_f32_e32 v155, v33
	v_exp_f32_e32 v164, v34
	v_exp_f32_e32 v167, v35
	v_add_u32_e32 v18, 0, v58
	v_lshl_add_u64 v[160:161], v[4:5], 0, v[50:51]
	v_lshl_add_u64 v[4:5], s[42:43], 0, v[48:49]
	v_lshlrev_b32_e32 v2, 4, v2
	v_mov_b32_e32 v16, v3
	v_mov_b32_e32 v17, v3
	v_and_b32_e32 v156, 0xffffffe0, v56
	v_cndmask_b32_e64 v184, v20, 1.0, vcc
	v_cmp_gt_u32_e64 s[10:11], 32, v37
	v_lshl_add_u64 v[162:163], v[4:5], 0, v[2:3]
	v_mov_b32_e32 v2, v3
	v_mov_b32_e32 v4, v3
	v_mov_b32_e32 v5, v3
	v_mov_b32_e32 v6, v3
	v_mov_b32_e32 v7, v3
	v_mov_b32_e32 v8, v3
	v_mov_b32_e32 v9, v3
	v_mov_b32_e32 v10, v3
	v_mov_b32_e32 v11, v3
	v_mov_b32_e32 v12, v3
	v_mov_b32_e32 v13, v3
	v_mov_b32_e32 v14, v3
	v_mov_b32_e32 v15, v3
	v_add_u32_e32 v186, v18, v36
	v_mov_b64_e32 v[66:67], v[16:17]
	v_mov_b64_e32 v[50:51], v[16:17]
	v_mov_b64_e32 v[34:35], v[16:17]
	v_mov_b64_e32 v[64:65], v[14:15]
	v_mov_b64_e32 v[62:63], v[12:13]
	v_mov_b64_e32 v[60:61], v[10:11]
	v_mov_b64_e32 v[58:59], v[8:9]
	v_mov_b64_e32 v[56:57], v[6:7]
	v_mov_b64_e32 v[54:55], v[4:5]
	v_mov_b64_e32 v[52:53], v[2:3]
	v_mov_b64_e32 v[48:49], v[14:15]
	v_mov_b64_e32 v[46:47], v[12:13]
	v_mov_b64_e32 v[44:45], v[10:11]
	v_mov_b64_e32 v[42:43], v[8:9]
	v_mov_b64_e32 v[40:41], v[6:7]
	v_mov_b64_e32 v[38:39], v[4:5]
	v_mov_b64_e32 v[36:37], v[2:3]
	v_mov_b64_e32 v[32:33], v[14:15]
	v_mov_b64_e32 v[30:31], v[12:13]
	v_mov_b64_e32 v[28:29], v[10:11]
	v_mov_b64_e32 v[26:27], v[8:9]
	v_mov_b64_e32 v[24:25], v[6:7]
	v_mov_b64_e32 v[22:23], v[4:5]
	v_mov_b64_e32 v[20:21], v[2:3]
	v_mov_b64_e32 v[18:19], v[16:17]
	v_lshl_add_u32 v175, v172, 2, v157
	v_lshlrev_b32_e32 v174, 4, v173
	v_mov_b32_e32 v177, 0
	s_mov_b32 s44, -1
	v_mov_b64_e32 v[16:17], v[14:15]
	v_mov_b64_e32 v[14:15], v[12:13]
	v_mov_b64_e32 v[12:13], v[10:11]
	v_mov_b64_e32 v[10:11], v[8:9]
	v_mov_b64_e32 v[8:9], v[6:7]
	v_mov_b64_e32 v[6:7], v[4:5]
	v_mov_b64_e32 v[4:5], v[2:3]
	s_waitcnt lgkmcnt(0)
	s_barrier

.LBB0_2422:
	v_cndmask_b32_e64 v185, v128, v185, s[14:15]
	v_mul_f32_e32 v138, 0xbdd53b94, v185
	v_pk_fma_f32 v[84:85], v[84:85], s[34:35], v[138:139] op_sel_hi:[1,0,0]
	v_pk_fma_f32 v[86:87], v[86:87], s[34:35], v[138:139] op_sel_hi:[1,0,0]
	v_pk_fma_f32 v[88:89], v[88:89], s[34:35], v[138:139] op_sel_hi:[1,0,0]
	v_pk_fma_f32 v[90:91], v[90:91], s[34:35], v[138:139] op_sel_hi:[1,0,0]
	v_pk_fma_f32 v[92:93], v[92:93], s[34:35], v[138:139] op_sel_hi:[1,0,0]
	v_pk_fma_f32 v[94:95], v[94:95], s[34:35], v[138:139] op_sel_hi:[1,0,0]
	v_pk_fma_f32 v[96:97], v[96:97], s[34:35], v[138:139] op_sel_hi:[1,0,0]
	v_pk_fma_f32 v[98:99], v[98:99], s[34:35], v[138:139] op_sel_hi:[1,0,0]
	v_exp_f32_e32 v131, v84
	v_exp_f32_e32 v134, v85
	v_exp_f32_e32 v135, v86
	v_exp_f32_e32 v139, v87
	v_exp_f32_e32 v142, v88
	v_exp_f32_e32 v143, v89
	v_exp_f32_e32 v144, v90
	v_exp_f32_e32 v145, v91
	v_exp_f32_e32 v128, v92
	v_exp_f32_e32 v129, v93
	v_exp_f32_e32 v130, v94
	v_exp_f32_e32 v132, v95
	v_exp_f32_e32 v133, v96
	v_exp_f32_e32 v136, v97
	v_exp_f32_e32 v137, v98
	v_exp_f32_e32 v147, v99
	v_pk_fma_f32 v[140:141], v[68:69], s[34:35], v[138:139] op_sel_hi:[1,0,0]
	v_fmamk_f32 v146, v70, 0x3dd53b94, v138
	v_fmamk_f32 v148, v71, 0x3dd53b94, v138
	v_fmamk_f32 v149, v72, 0x3dd53b94, v138
	v_fmamk_f32 v150, v73, 0x3dd53b94, v138
	v_fmamk_f32 v151, v74, 0x3dd53b94, v138
	v_fmamk_f32 v152, v75, 0x3dd53b94, v138
	v_fmamk_f32 v153, v76, 0x3dd53b94, v138
	v_fmamk_f32 v154, v77, 0x3dd53b94, v138
	v_fmamk_f32 v155, v78, 0x3dd53b94, v138
	v_fmamk_f32 v189, v79, 0x3dd53b94, v138
	v_pk_fma_f32 v[190:191], v[80:81], s[34:35], v[138:139] op_sel_hi:[1,0,0]
	v_fmamk_f32 v192, v82, 0x3dd53b94, v138
	v_fmac_f32_e32 v138, 0x3dd53b94, v83
	s_waitcnt lgkmcnt(0)
	s_barrier
	s_nop 1
	ds_read_b128 v[194:197], v181
	ds_read_b128 v[202:205], v181 offset:6144
	ds_read_b128 v[198:201], v182
	ds_read_b128 v[206:209], v182 offset:6144
	v_exp_f32_e32 v193, v140
	v_add_f32_e32 v140, 0, v131
	v_add_f32_e32 v140, v134, v140
	v_add_f32_e32 v140, v135, v140
	v_add_f32_e32 v140, v139, v140
	s_waitcnt lgkmcnt(1)
	v_mfma_scale_f32_32x32x64_f8f6f4 v[84:99], v[194:201], v[116:123], 0, v170, v170 op_sel_hi:[0,0,0]
	s_waitcnt lgkmcnt(0)
	v_mfma_scale_f32_32x32x64_f8f6f4 v[68:83], v[202:209], v[116:123], 0, v170, v170 op_sel_hi:[0,0,0]
	ds_read_b128 v[194:197], v181 offset:64
	ds_read_b128 v[202:205], v181 offset:6208
	ds_read_b128 v[198:201], v182 offset:64
	ds_read_b128 v[206:209], v182 offset:6208
	v_add_f32_e32 v140, v142, v140
	v_add_f32_e32 v140, v143, v140
	v_add_f32_e32 v140, v144, v140
	v_add_f32_e32 v140, v145, v140
	v_add_f32_e32 v140, v128, v140
	s_waitcnt lgkmcnt(1)
	v_mfma_scale_f32_32x32x64_f8f6f4 v[84:99], v[194:201], v[108:115], v[84:99], v170, v170 op_sel_hi:[0,0,0]
	s_waitcnt lgkmcnt(0)
	v_mfma_scale_f32_32x32x64_f8f6f4 v[68:83], v[202:209], v[108:115], v[68:83], v170, v170 op_sel_hi:[0,0,0]
	ds_read_b128 v[194:197], v181 offset:128
	ds_read_b128 v[202:205], v181 offset:6272
	ds_read_b128 v[198:201], v182 offset:128
	ds_read_b128 v[206:209], v182 offset:6272
	v_add_f32_e32 v140, v129, v140
	v_add_f32_e32 v140, v130, v140
	v_add_f32_e32 v140, v132, v140
	v_add_f32_e32 v140, v133, v140
	s_waitcnt lgkmcnt(1)
	v_mfma_scale_f32_32x32x64_f8f6f4 v[84:99], v[194:201], v[100:107], v[84:99], v170, v170 op_sel_hi:[0,0,0]
	v_exp_f32_e32 v194, v141
	v_add_f32_e32 v140, v136, v140
	v_exp_f32_e32 v195, v146
	v_add_f32_e32 v140, v137, v140
	v_exp_f32_e32 v196, v148
	v_add_f32_e32 v140, v147, v140
	v_exp_f32_e32 v197, v149
	v_add_f32_e32 v140, v193, v140
	v_exp_f32_e32 v150, v150
	v_add_f32_e32 v140, v194, v140
	v_exp_f32_e32 v151, v151
	v_add_f32_e32 v140, v195, v140
	v_exp_f32_e32 v152, v152
	v_add_f32_e32 v140, v196, v140
	v_exp_f32_e32 v153, v153
	v_add_f32_e32 v140, v197, v140
	v_exp_f32_e32 v154, v154
	v_add_f32_e32 v140, v150, v140
	v_exp_f32_e32 v155, v155
	v_add_f32_e32 v140, v151, v140
	v_exp_f32_e32 v198, v189
	v_add_f32_e32 v140, v152, v140
	v_exp_f32_e32 v199, v190
	v_add_f32_e32 v140, v153, v140
	v_exp_f32_e32 v191, v191
	v_add_f32_e32 v140, v154, v140
	v_exp_f32_e32 v192, v192
	v_add_f32_e32 v140, v155, v140
	v_exp_f32_e32 v138, v138
	v_add_f32_e32 v140, v198, v140
	v_add_f32_e32 v140, v199, v140
	v_add_f32_e32 v140, v191, v140
	v_add_f32_e32 v140, v192, v140
	v_add_f32_e32 v189, v138, v140
	v_mov_b32_e32 v190, v189
	v_cvt_pk_bf16_f32 v140, v131, v134
	v_cvt_pk_bf16_f32 v141, v135, v139
	v_cvt_pk_bf16_f32 v142, v142, v143
	v_cvt_pk_bf16_f32 v143, v144, v145
	v_cvt_pk_bf16_f32 v144, v128, v129
	v_cvt_pk_bf16_f32 v145, v130, v132
	v_cvt_pk_bf16_f32 v146, v133, v136
	v_cvt_pk_bf16_f32 v147, v137, v147
	v_cvt_pk_bf16_f32 v148, v193, v194
	v_cvt_pk_bf16_f32 v149, v195, v196
	v_cvt_pk_bf16_f32 v150, v197, v150
	v_cvt_pk_bf16_f32 v151, v151, v152
	v_cvt_pk_bf16_f32 v152, v153, v154
	v_cvt_pk_bf16_f32 v153, v155, v198
	v_cvt_pk_bf16_f32 v154, v199, v191
	v_cvt_pk_bf16_f32 v155, v192, v138
	s_waitcnt lgkmcnt(0)
	v_mfma_scale_f32_32x32x64_f8f6f4 v[68:83], v[202:209], v[100:107], v[68:83], v170, v170 op_sel_hi:[0,0,0]
	v_permlane32_swap_b32_e32 v189, v190
	v_permlane32_swap_b32_e32 v140, v142
	v_permlane32_swap_b32_e32 v141, v143
	v_permlane32_swap_b32_e32 v144, v146
	v_permlane32_swap_b32_e32 v145, v147
	v_permlane32_swap_b32_e32 v148, v150
	v_permlane32_swap_b32_e32 v149, v151
	v_permlane32_swap_b32_e32 v152, v154
	v_permlane32_swap_b32_e32 v153, v155
	s_nop 15
	s_nop 15
	s_mov_b32 s0, 0x2a10c000
	v_add_co_u32_e32 v128, vcc, s0, v166
	s_nop 1
	v_addc_co_u32_e32 v129, vcc, 0, v167, vcc
	v_add_co_u32_e32 v132, vcc, 0x2a10e000, v166
	s_nop 1
	v_addc_co_u32_e32 v133, vcc, 0, v167, vcc
	v_add_co_u32_e32 v136, vcc, 0x1e109000, v168
	global_load_dwordx4 v[128:131], v[128:129], off
	s_nop 0
	global_load_dwordx4 v[132:135], v[132:133], off
	v_addc_co_u32_e32 v137, vcc, 0, v169, vcc
	global_load_dwordx4 v[136:139], v[136:137], off
	s_and_saveexec_b64 s[14:15], s[12:13]
	s_cbranch_execz .LBB0_2424
	v_add_co_u32_e32 v124, vcc, 0x1e109000, v164
	s_nop 1
	v_addc_co_u32_e32 v125, vcc, 0, v165, vcc
	global_load_dwordx4 v[124:127], v[124:125], off

.LBB0_2430:
	v_cndmask_b32_e64 v185, v128, v185, s[14:15]
	v_mul_f32_e32 v132, 0xbdd53b94, v185
	v_mov_b32_e32 v133, v132
	v_pk_fma_f32 v[84:85], v[84:85], s[34:35], v[132:133] op_sel_hi:[1,0,0]
	v_pk_fma_f32 v[86:87], v[86:87], s[34:35], v[132:133] op_sel_hi:[1,0,0]
	v_pk_fma_f32 v[88:89], v[88:89], s[34:35], v[132:133] op_sel_hi:[1,0,0]
	v_pk_fma_f32 v[90:91], v[90:91], s[34:35], v[132:133] op_sel_hi:[1,0,0]
	v_pk_fma_f32 v[92:93], v[92:93], s[34:35], v[132:133] op_sel_hi:[1,0,0]
	v_pk_fma_f32 v[94:95], v[94:95], s[34:35], v[132:133] op_sel_hi:[1,0,0]
	v_pk_fma_f32 v[96:97], v[96:97], s[34:35], v[132:133] op_sel_hi:[1,0,0]
	v_fmamk_f32 v98, v98, 0x3dd53b94, v132
	v_fmac_f32_e32 v133, 0x3dd53b94, v99
	v_exp_f32_e32 v150, v84
	v_exp_f32_e32 v151, v85
	v_exp_f32_e32 v152, v86
	v_exp_f32_e32 v153, v87
	v_exp_f32_e32 v154, v88
	v_exp_f32_e32 v165, v89
	v_exp_f32_e32 v166, v90
	v_exp_f32_e32 v168, v91
	v_exp_f32_e32 v145, v92
	v_exp_f32_e32 v146, v93
	v_exp_f32_e32 v147, v94
	v_exp_f32_e32 v148, v95
	v_exp_f32_e32 v149, v96
	v_exp_f32_e32 v155, v97
	v_exp_f32_e32 v164, v98
	v_exp_f32_e32 v167, v133
	v_add_f32_e32 v2, v2, v187
	v_fmac_f32_e32 v2, v184, v177
	v_add_f32_e32 v177, v189, v190
	s_add_i32 s44, s44, 2
	s_mov_b64 s[0:1], 0x8000
	v_pk_fma_f32 v[140:141], v[68:69], s[34:35], v[132:133] op_sel_hi:[1,0,0]
	v_pk_fma_f32 v[136:137], v[70:71], s[34:35], v[132:133] op_sel_hi:[1,0,0]
	v_pk_fma_f32 v[134:135], v[72:73], s[34:35], v[132:133] op_sel_hi:[1,0,0]
	v_pk_fma_f32 v[130:131], v[74:75], s[34:35], v[132:133] op_sel_hi:[1,0,0]
	v_pk_fma_f32 v[128:129], v[76:77], s[34:35], v[132:133] op_sel_hi:[1,0,0]
	v_pk_fma_f32 v[142:143], v[78:79], s[34:35], v[132:133] op_sel_hi:[1,0,0]
	v_pk_fma_f32 v[138:139], v[80:81], s[34:35], v[132:133] op_sel_hi:[1,0,0]
	v_pk_fma_f32 v[132:133], v[82:83], s[34:35], v[132:133] op_sel_hi:[1,0,0]
	v_fmac_f32_e32 v177, v2, v188
	v_lshl_add_u64 v[158:159], v[158:159], 0, s[36:37]
	v_lshl_add_u64 v[160:161], v[160:161], 0, s[36:37]
	s_cmp_gt_u32 s44, 28
	v_lshl_add_u64 v[162:163], v[162:163], 0, s[0:1]
	s_waitcnt lgkmcnt(0)
	s_barrier
	s_cbranch_scc1 .LBB0_2432
	v_mov_b32_e32 v184, v144
	s_branch .LBB0_2414

.LBB0_2436:
	v_cndmask_b32_e64 v102, v102, v185, s[12:13]
	v_mul_f32_e32 v102, 0xbdd53b94, v102
	v_pk_fma_f32 v[84:85], v[84:85], s[34:35], v[102:103] op_sel_hi:[1,0,0]
	v_fmamk_f32 v111, v97, 0x3dd53b94, v102
	v_fmamk_f32 v97, v78, 0x3dd53b94, v102
	v_exp_f32_e32 v78, v84
	v_fmamk_f32 v86, v86, 0x3dd53b94, v102
	v_fmamk_f32 v112, v98, 0x3dd53b94, v102
	v_fmamk_f32 v98, v79, 0x3dd53b94, v102
	v_exp_f32_e32 v79, v85
	v_fmamk_f32 v87, v87, 0x3dd53b94, v102
	v_fmamk_f32 v113, v99, 0x3dd53b94, v102
	v_fmamk_f32 v99, v80, 0x3dd53b94, v102
	v_exp_f32_e32 v80, v86
	v_fmamk_f32 v88, v88, 0x3dd53b94, v102
	v_fmamk_f32 v68, v68, 0x3dd53b94, v102
	v_exp_f32_e32 v84, v87
	v_fmamk_f32 v103, v89, 0x3dd53b94, v102
	v_pk_fma_f32 v[104:105], v[90:91], s[34:35], v[102:103] op_sel_hi:[1,0,0]
	v_pk_fma_f32 v[106:107], v[92:93], s[34:35], v[102:103] op_sel_hi:[1,0,0]
	v_pk_fma_f32 v[108:109], v[94:95], s[34:35], v[102:103] op_sel_hi:[1,0,0]
	v_fmamk_f32 v110, v96, 0x3dd53b94, v102
	v_fmamk_f32 v69, v69, 0x3dd53b94, v102
	v_fmamk_f32 v89, v70, 0x3dd53b94, v102
	v_fmamk_f32 v90, v71, 0x3dd53b94, v102
	v_fmamk_f32 v91, v72, 0x3dd53b94, v102
	v_fmamk_f32 v92, v73, 0x3dd53b94, v102
	v_fmamk_f32 v93, v74, 0x3dd53b94, v102
	v_fmamk_f32 v94, v75, 0x3dd53b94, v102
	v_fmamk_f32 v95, v76, 0x3dd53b94, v102
	v_fmamk_f32 v96, v77, 0x3dd53b94, v102
	v_exp_f32_e32 v85, v88
	v_fmamk_f32 v81, v81, 0x3dd53b94, v102
	v_fmamk_f32 v82, v82, 0x3dd53b94, v102
	v_fmac_f32_e32 v102, 0x3dd53b94, v83
	v_exp_f32_e32 v83, v68
	v_add_f32_e32 v68, 0, v78
	v_exp_f32_e32 v86, v103
	v_add_f32_e32 v68, v79, v68
	v_exp_f32_e32 v87, v104
	v_add_f32_e32 v68, v80, v68
	v_exp_f32_e32 v88, v105
	v_add_f32_e32 v68, v84, v68
	v_exp_f32_e32 v70, v106
	v_add_f32_e32 v68, v85, v68
	v_exp_f32_e32 v71, v107
	v_add_f32_e32 v68, v86, v68
	v_exp_f32_e32 v72, v108
	v_add_f32_e32 v68, v87, v68
	v_exp_f32_e32 v73, v109
	v_add_f32_e32 v68, v88, v68
	v_exp_f32_e32 v74, v110
	v_add_f32_e32 v68, v70, v68
	v_exp_f32_e32 v75, v111
	v_add_f32_e32 v68, v71, v68
	v_exp_f32_e32 v76, v112
	v_add_f32_e32 v68, v72, v68
	v_exp_f32_e32 v77, v113
	v_add_f32_e32 v68, v73, v68
	v_add_f32_e32 v68, v74, v68
	v_exp_f32_e32 v103, v69
	v_add_f32_e32 v68, v75, v68
	v_exp_f32_e32 v89, v89
	v_add_f32_e32 v68, v76, v68
	v_exp_f32_e32 v90, v90
	v_add_f32_e32 v68, v77, v68
	v_exp_f32_e32 v91, v91
	v_add_f32_e32 v68, v83, v68
	v_exp_f32_e32 v92, v92
	v_add_f32_e32 v68, v103, v68
	v_exp_f32_e32 v93, v93
	v_add_f32_e32 v68, v89, v68
	v_exp_f32_e32 v94, v94
	v_add_f32_e32 v68, v90, v68
	v_exp_f32_e32 v95, v95
	v_add_f32_e32 v68, v91, v68
	v_exp_f32_e32 v96, v96
	v_add_f32_e32 v68, v92, v68
	v_exp_f32_e32 v97, v97
	v_add_f32_e32 v68, v93, v68
	v_exp_f32_e32 v98, v98
	v_add_f32_e32 v68, v94, v68
	v_exp_f32_e32 v99, v99
	v_add_f32_e32 v68, v95, v68
	v_exp_f32_e32 v104, v81
	v_add_f32_e32 v68, v96, v68
	v_exp_f32_e32 v105, v82
	v_add_f32_e32 v68, v97, v68
	v_exp_f32_e32 v102, v102
	v_add_f32_e32 v68, v98, v68
	v_add_f32_e32 v68, v99, v68
	v_add_f32_e32 v68, v104, v68
	v_add_f32_e32 v68, v105, v68
	v_add_f32_e32 v68, v102, v68
	v_mov_b32_e32 v69, v68
	s_nop 1
	v_permlane32_swap_b32_e32 v68, v69
	v_cvt_pk_bf16_f32 v78, v78, v79
	v_cvt_pk_bf16_f32 v79, v80, v84
	v_cvt_pk_bf16_f32 v80, v85, v86
	v_cvt_pk_bf16_f32 v81, v87, v88
	v_cvt_pk_bf16_f32 v70, v70, v71
	v_cvt_pk_bf16_f32 v71, v72, v73
	v_cvt_pk_bf16_f32 v72, v74, v75
	v_cvt_pk_bf16_f32 v73, v76, v77
	v_cvt_pk_bf16_f32 v74, v83, v103
	v_cvt_pk_bf16_f32 v75, v89, v90
	v_cvt_pk_bf16_f32 v76, v91, v92
	v_cvt_pk_bf16_f32 v77, v93, v94
	v_cvt_pk_bf16_f32 v82, v95, v96
	v_cvt_pk_bf16_f32 v83, v97, v98
	v_cvt_pk_bf16_f32 v84, v99, v104
	v_cvt_pk_bf16_f32 v85, v105, v102
	v_permlane32_swap_b32_e32 v78, v80
	v_permlane32_swap_b32_e32 v79, v81
	v_permlane32_swap_b32_e32 v70, v72
	v_permlane32_swap_b32_e32 v71, v73
	v_permlane32_swap_b32_e32 v74, v76
	v_permlane32_swap_b32_e32 v75, v77
	v_permlane32_swap_b32_e32 v82, v84
	v_permlane32_swap_b32_e32 v83, v85
	ds_read_b64_tr_b16 v[86:87], v176 offset:0
	ds_read_b64_tr_b16 v[88:89], v176 offset:0x800
	ds_read_b64_tr_b16 v[90:91], v176 offset:0x1000
	ds_read_b64_tr_b16 v[92:93], v176 offset:0x1800
	ds_read_b64_tr_b16 v[94:95], v176 offset:0x2000
	ds_read_b64_tr_b16 v[96:97], v176 offset:0x2800
	ds_read_b64_tr_b16 v[102:103], v176 offset:0x3000
	ds_read_b64_tr_b16 v[104:105], v176 offset:0x3800
	s_waitcnt lgkmcnt(0)
	s_nop 0
	v_mfma_f32_32x32x16_bf16 v[52:67], v[78:81], v[86:89], v[52:67]
	ds_read_b64_tr_b16 v[86:87], v176 offset:0x200
	ds_read_b64_tr_b16 v[88:89], v176 offset:0xa00
	v_mfma_f32_32x32x16_bf16 v[52:67], v[70:73], v[90:93], v[52:67]
	ds_read_b64_tr_b16 v[90:91], v176 offset:0x1200
	ds_read_b64_tr_b16 v[92:93], v176 offset:0x1a00
	v_mfma_f32_32x32x16_bf16 v[52:67], v[74:77], v[94:97], v[52:67]
	ds_read_b64_tr_b16 v[94:95], v176 offset:0x2200
	ds_read_b64_tr_b16 v[96:97], v176 offset:0x2a00
	v_mfma_f32_32x32x16_bf16 v[52:67], v[82:85], v[102:105], v[52:67]
	ds_read_b64_tr_b16 v[102:103], v176 offset:0x3200
	ds_read_b64_tr_b16 v[104:105], v176 offset:0x3a00
	s_waitcnt lgkmcnt(0)
	v_mfma_f32_32x32x16_bf16 v[36:51], v[78:81], v[86:89], v[36:51]
	ds_read_b64_tr_b16 v[86:87], v176 offset:0x400
	ds_read_b64_tr_b16 v[88:89], v176 offset:0xc00
	v_mfma_f32_32x32x16_bf16 v[36:51], v[70:73], v[90:93], v[36:51]
	ds_read_b64_tr_b16 v[90:91], v176 offset:0x1400
	ds_read_b64_tr_b16 v[92:93], v176 offset:0x1c00
	v_mfma_f32_32x32x16_bf16 v[36:51], v[74:77], v[94:97], v[36:51]
	ds_read_b64_tr_b16 v[94:95], v176 offset:0x2400
	ds_read_b64_tr_b16 v[96:97], v176 offset:0x2c00
	v_mfma_f32_32x32x16_bf16 v[36:51], v[82:85], v[102:105], v[36:51]
	ds_read_b64_tr_b16 v[102:103], v176 offset:0x3400
	ds_read_b64_tr_b16 v[104:105], v176 offset:0x3c00
	s_waitcnt lgkmcnt(0)
	v_mfma_f32_32x32x16_bf16 v[20:35], v[78:81], v[86:89], v[20:35]
	ds_read_b64_tr_b16 v[86:87], v176 offset:0x600
	ds_read_b64_tr_b16 v[88:89], v176 offset:0xe00
	v_mfma_f32_32x32x16_bf16 v[20:35], v[70:73], v[90:93], v[20:35]
	ds_read_b64_tr_b16 v[90:91], v176 offset:0x1600
	ds_read_b64_tr_b16 v[92:93], v176 offset:0x1e00
	v_mfma_f32_32x32x16_bf16 v[20:35], v[74:77], v[94:97], v[20:35]
	ds_read_b64_tr_b16 v[94:95], v176 offset:0x2600
	ds_read_b64_tr_b16 v[96:97], v176 offset:0x2e00
	v_mfma_f32_32x32x16_bf16 v[20:35], v[82:85], v[102:105], v[20:35]
	ds_read_b64_tr_b16 v[102:103], v176 offset:0x3600
	ds_read_b64_tr_b16 v[104:105], v176 offset:0x3e00
	s_waitcnt lgkmcnt(0)
	v_mfma_f32_32x32x16_bf16 v[4:19], v[78:81], v[86:89], v[4:19]
	v_mfma_f32_32x32x16_bf16 v[4:19], v[70:73], v[90:93], v[4:19]
	v_mfma_f32_32x32x16_bf16 v[4:19], v[74:77], v[94:97], v[4:19]
	v_mfma_f32_32x32x16_bf16 v[4:19], v[82:85], v[102:105], v[4:19]
	s_and_saveexec_b64 s[12:13], s[10:11]
	s_cbranch_execz .LBB0_2404
	v_add_f32_e32 v2, v2, v100
	v_fmac_f32_e32 v2, v177, v144
	v_add_f32_e32 v68, v68, v69
	v_fmac_f32_e32 v68, v2, v101
	ds_write_b32 v175, v68 offset:57344
	s_branch .LBB0_2404
